# chunk-MLP filler items re-split 1/4 (P3) and 0/5 (P5) per workgroup half, LN statistics recomputed when an item starts a new chunk; nop pads keep GEMM loop-head alignment
# baseline (speedup 1.0000x reference)
.LBB0_682:
	s_mul_i32 s5, s2, 1
	s_add_i32 s5, s5, 0
	s_mov_b32 s3, 1
	s_cmpk_lt_i32 s2, 0x80
	s_cbranch_scc1 .Lcma_hd
	s_mul_i32 s5, s2, 4
	s_add_i32 s5, s5, -384
	s_mov_b32 s3, 4

.Lcma_top:
	s_waitcnt vmcnt(8)
	s_and_b32 s0, s5, 7
	s_cmp_lg_u32 s0, 0
	s_cbranch_scc1 .Lcma_copy
.Lcma_stats:
	v_readfirstlane_b32 s0, v195
	s_nop 1
	s_cmp_lt_u32 s0, 0x80
	s_cbranch_scc0 .Lcma_nostat
	v_pk_add_f32 v[56:57], v[132:133], v[134:135]
	v_pk_add_f32 v[60:61], v[136:137], v[138:139]
	v_pk_add_f32 v[56:57], v[56:57], 0 op_sel_hi:[1,0]
	v_pk_add_f32 v[58:59], v[140:141], v[142:143]
	v_pk_add_f32 v[56:57], v[56:57], v[60:61]
	v_pk_add_f32 v[60:61], v[144:145], v[146:147]
	v_pk_add_f32 v[56:57], v[56:57], v[58:59]
	v_pk_add_f32 v[58:59], v[148:149], v[150:151]
	v_pk_add_f32 v[56:57], v[56:57], v[60:61]
	v_pk_add_f32 v[60:61], v[152:153], v[154:155]
	v_pk_add_f32 v[56:57], v[56:57], v[58:59]
	v_pk_add_f32 v[58:59], v[156:157], v[158:159]
	v_pk_add_f32 v[56:57], v[56:57], v[60:61]
	v_pk_add_f32 v[60:61], v[160:161], v[162:163]
	v_pk_add_f32 v[56:57], v[56:57], v[58:59]
	s_nop 0
	v_pk_add_f32 v[56:57], v[56:57], v[60:61]
	s_nop 0
	v_pk_mul_f32 v[56:57], v[56:57], s[4:5] op_sel_hi:[1,0]
	s_nop 0
	v_fma_f32 v58, -v56, v56, v57
	v_max_f32_e32 v58, 0, v58
	v_add_f32_e32 v58, 0x358637bd, v58
	v_rsq_f32_e32 v57, v58
	s_nop 1
	ds_write_b64 v215, v[56:57]
.Lcma_nostat:
.Lcma_copy:
	s_mov_b64 s[12:13], s[6:7]
	v_mov_b32_e32 v0, v100
	v_mov_b32_e32 v1, v101
	v_mov_b32_e32 v2, v102
	v_mov_b32_e32 v3, v103
	v_mov_b32_e32 v4, v104
	v_mov_b32_e32 v5, v105
	v_mov_b32_e32 v6, v106
	v_mov_b32_e32 v7, v107
	v_mov_b32_e32 v8, v108
	v_mov_b32_e32 v9, v109
	v_mov_b32_e32 v10, v110
	v_mov_b32_e32 v11, v111
	v_mov_b32_e32 v12, v112
	v_mov_b32_e32 v13, v113
	v_mov_b32_e32 v14, v114
	v_mov_b32_e32 v15, v115
	v_mov_b32_e32 v16, v116
	v_mov_b32_e32 v17, v117
	v_mov_b32_e32 v18, v118
	v_mov_b32_e32 v19, v119
	v_mov_b32_e32 v20, v120
	v_mov_b32_e32 v21, v121
	v_mov_b32_e32 v22, v122
	v_mov_b32_e32 v23, v123
	v_mov_b32_e32 v24, v124
	v_mov_b32_e32 v25, v125
	v_mov_b32_e32 v26, v126
	v_mov_b32_e32 v27, v127
	v_mov_b32_e32 v28, v128
	v_mov_b32_e32 v29, v129
	v_mov_b32_e32 v30, v130
	v_mov_b32_e32 v31, v131
	v_mov_b32_e32 v38, v164
	v_mov_b32_e32 v39, v165
	v_mov_b32_e32 v40, v166
	v_mov_b32_e32 v41, v167
	v_mov_b32_e32 v42, v168
	v_mov_b32_e32 v43, v169
	v_mov_b32_e32 v44, v170
	v_mov_b32_e32 v45, v171
	v_mov_b32_e32 v46, v172
	v_mov_b32_e32 v47, v173
	v_mov_b32_e32 v48, v174
	v_mov_b32_e32 v49, v175
	v_mov_b32_e32 v50, v176
	v_mov_b32_e32 v51, v177
	v_mov_b32_e32 v52, v178
	v_mov_b32_e32 v53, v179
	v_mov_b32_e32 v70, v220
	v_mov_b32_e32 v71, v221
	v_mov_b32_e32 v72, v222
	v_mov_b32_e32 v73, v223
	v_mov_b32_e32 v74, v224
	v_mov_b32_e32 v75, v225
	v_mov_b32_e32 v76, v226
	v_mov_b32_e32 v77, v227
	v_mov_b32_e32 v78, v228
	v_mov_b32_e32 v79, v229
	v_mov_b32_e32 v80, v230
	v_mov_b32_e32 v81, v231
	v_mov_b32_e32 v82, v232
	v_mov_b32_e32 v83, v233
	v_mov_b32_e32 v84, v234
	v_mov_b32_e32 v85, v235
	v_mov_b32_e32 v86, v236
	s_cmp_gt_u32 s3, 1
	s_cbranch_scc0 .Lcma_nopf
	s_add_i32 s0, s5, 1
	s_and_b32 s1, s0, 7
	s_lshr_b32 s0, s0, 3
	s_lshl_b32 s0, s0, 7
	s_lshl_b32 s10, s1, 8
	s_lshl_b32 s11, s0, 11
	s_add_u32 s11, s11, s10
	s_add_u32 s46, s42, s11
	s_addc_u32 s47, s43, 0
	s_add_u32 s6, s96, s11
	s_addc_u32 s7, s97, 0
	s_lshl_b32 s10, s1, 15
	s_add_u32 s48, s8, s10
	s_addc_u32 s49, s9, 0
	s_lshl_b32 s10, s0, 7
	s_add_u32 s50, s44, s10
	s_addc_u32 s51, s45, 0
	s_lshl_b32 s10, s1, 9
	s_add_u32 s14, s36, s10
	s_addc_u32 s15, s37, 0
	s_add_u32 s16, s38, s10
	s_addc_u32 s17, s39, 0
	s_add_u32 s10, s40, s10
	s_addc_u32 s11, s41, 0
	s_cmp_lg_u32 s1, 0
	s_cbranch_scc1 .Lcma_pf1
	v_readfirstlane_b32 s0, v195
	s_nop 1
	s_cmp_lt_u32 s0, 0x80
	s_cbranch_scc0 .Lcma_pf1
	global_load_dwordx4 v[132:135], v208, s[50:51]
	global_load_dwordx4 v[136:139], v208, s[50:51] offset:16
	global_load_dwordx4 v[140:143], v208, s[50:51] offset:32
	global_load_dwordx4 v[144:147], v208, s[50:51] offset:48
	global_load_dwordx4 v[148:151], v208, s[50:51] offset:64
	global_load_dwordx4 v[152:155], v208, s[50:51] offset:80
	global_load_dwordx4 v[156:159], v208, s[50:51] offset:96
	global_load_dwordx4 v[160:163], v208, s[50:51] offset:112
.Lcma_pf1:
	global_load_dwordx4 v[100:103], v200, s[46:47]
	global_load_dwordx4 v[116:119], v204, s[48:49]
	global_load_dwordx4 v[104:107], v201, s[46:47]
	global_load_dwordx4 v[120:123], v205, s[48:49]
	global_load_dwordx4 v[108:111], v202, s[46:47]
	global_load_dwordx4 v[124:127], v206, s[48:49]
	global_load_dwordx4 v[112:115], v203, s[46:47]
	global_load_dwordx4 v[128:131], v207, s[48:49]
	global_load_dwordx4 v[164:167], v209, s[14:15]
	global_load_dwordx4 v[168:171], v209, s[16:17]
	global_load_dwordx4 v[172:175], v209, s[16:17] offset:16
	global_load_dwordx4 v[176:179], v209, s[14:15] offset:16
	global_load_dword v236, v210, s[10:11]
	global_load_dwordx2 v[220:221], v211, s[6:7]
	global_load_dwordx2 v[222:223], v211, s[6:7] offset:32
	global_load_dwordx2 v[224:225], v211, s[6:7] offset:64
	global_load_dwordx2 v[226:227], v211, s[6:7] offset:96
	global_load_dwordx2 v[228:229], v211, s[6:7] offset:128
	global_load_dwordx2 v[230:231], v211, s[6:7] offset:160
	global_load_dwordx2 v[232:233], v211, s[6:7] offset:192
	global_load_dwordx2 v[234:235], v211, s[6:7] offset:224
.Lcma_nopf:
	s_waitcnt lgkmcnt(0)
	s_barrier
	ds_read_b64 v[88:89], v214
	ds_read_b64 v[90:91], v214 offset:256
	ds_read_b64 v[92:93], v214 offset:512
	ds_read_b64 v[94:95], v214 offset:768
	s_waitcnt lgkmcnt(3)
	v_lshlrev_b32_e32 v56, 16, v0
	v_and_b32_e32 v57, 0xffff0000, v0
	v_lshlrev_b32_e32 v58, 16, v1
	v_and_b32_e32 v59, 0xffff0000, v1
	v_lshlrev_b32_e32 v60, 16, v2
	v_and_b32_e32 v61, 0xffff0000, v2
	v_lshlrev_b32_e32 v62, 16, v3
	v_and_b32_e32 v63, 0xffff0000, v3
	v_sub_f32_e32 v56, v56, v88
	v_sub_f32_e32 v57, v57, v88
	v_sub_f32_e32 v58, v58, v88
	v_sub_f32_e32 v59, v59, v88
	v_sub_f32_e32 v60, v60, v88
	v_sub_f32_e32 v61, v61, v88
	v_sub_f32_e32 v62, v62, v88
	v_sub_f32_e32 v63, v63, v88
	v_mul_f32_e32 v56, v89, v56
	v_mul_f32_e32 v57, v89, v57
	v_mul_f32_e32 v58, v89, v58
	v_mul_f32_e32 v59, v89, v59
	v_mul_f32_e32 v60, v89, v60
	v_mul_f32_e32 v61, v89, v61
	v_mul_f32_e32 v62, v89, v62
	v_mul_f32_e32 v63, v89, v63
	v_fma_f32 v56, v42, v56, v38
	v_fma_f32 v57, v43, v57, v39
	v_fma_f32 v58, v44, v58, v40
	v_fma_f32 v59, v45, v59, v41
	v_fma_f32 v60, v46, v60, v50
	v_fma_f32 v61, v47, v61, v51
	v_fma_f32 v62, v48, v62, v52
	v_fma_f32 v63, v49, v63, v53
	v_cvt_pk_bf16_f32 v64, v56, v57
	v_cvt_pk_bf16_f32 v65, v58, v59
	v_cvt_pk_bf16_f32 v66, v60, v61
	v_cvt_pk_bf16_f32 v67, v62, v63
	ds_write_b128 v212, v[64:67]
	ds_write_b128 v213, v[16:19]
	s_waitcnt lgkmcnt(4)
	v_lshlrev_b32_e32 v56, 16, v4
	v_and_b32_e32 v57, 0xffff0000, v4
	v_lshlrev_b32_e32 v58, 16, v5
	v_and_b32_e32 v59, 0xffff0000, v5
	v_lshlrev_b32_e32 v60, 16, v6
	v_and_b32_e32 v61, 0xffff0000, v6
	v_lshlrev_b32_e32 v62, 16, v7
	v_and_b32_e32 v63, 0xffff0000, v7
	v_sub_f32_e32 v56, v56, v90
	v_sub_f32_e32 v57, v57, v90
	v_sub_f32_e32 v58, v58, v90
	v_sub_f32_e32 v59, v59, v90
	v_sub_f32_e32 v60, v60, v90
	v_sub_f32_e32 v61, v61, v90
	v_sub_f32_e32 v62, v62, v90
	v_sub_f32_e32 v63, v63, v90
	v_mul_f32_e32 v56, v91, v56
	v_mul_f32_e32 v57, v91, v57
	v_mul_f32_e32 v58, v91, v58
	v_mul_f32_e32 v59, v91, v59
	v_mul_f32_e32 v60, v91, v60
	v_mul_f32_e32 v61, v91, v61
	v_mul_f32_e32 v62, v91, v62
	v_mul_f32_e32 v63, v91, v63
	v_fma_f32 v56, v42, v56, v38
	v_fma_f32 v57, v43, v57, v39
	v_fma_f32 v58, v44, v58, v40
	v_fma_f32 v59, v45, v59, v41
	v_fma_f32 v60, v46, v60, v50
	v_fma_f32 v61, v47, v61, v51
	v_fma_f32 v62, v48, v62, v52
	v_fma_f32 v63, v49, v63, v53
	v_cvt_pk_bf16_f32 v64, v56, v57
	v_cvt_pk_bf16_f32 v65, v58, v59
	v_cvt_pk_bf16_f32 v66, v60, v61
	v_cvt_pk_bf16_f32 v67, v62, v63
	ds_write_b128 v212, v[64:67] offset:9216
	ds_write_b128 v213, v[20:23] offset:8704
	s_waitcnt lgkmcnt(5)
	v_lshlrev_b32_e32 v56, 16, v8
	v_and_b32_e32 v57, 0xffff0000, v8
	v_lshlrev_b32_e32 v58, 16, v9
	v_and_b32_e32 v59, 0xffff0000, v9
	v_lshlrev_b32_e32 v60, 16, v10
	v_and_b32_e32 v61, 0xffff0000, v10
	v_lshlrev_b32_e32 v62, 16, v11
	v_and_b32_e32 v63, 0xffff0000, v11
	v_sub_f32_e32 v56, v56, v92
	v_sub_f32_e32 v57, v57, v92
	v_sub_f32_e32 v58, v58, v92
	v_sub_f32_e32 v59, v59, v92
	v_sub_f32_e32 v60, v60, v92
	v_sub_f32_e32 v61, v61, v92
	v_sub_f32_e32 v62, v62, v92
	v_sub_f32_e32 v63, v63, v92
	v_mul_f32_e32 v56, v93, v56
	v_mul_f32_e32 v57, v93, v57
	v_mul_f32_e32 v58, v93, v58
	v_mul_f32_e32 v59, v93, v59
	v_mul_f32_e32 v60, v93, v60
	v_mul_f32_e32 v61, v93, v61
	v_mul_f32_e32 v62, v93, v62
	v_mul_f32_e32 v63, v93, v63
	v_fma_f32 v56, v42, v56, v38
	v_fma_f32 v57, v43, v57, v39
	v_fma_f32 v58, v44, v58, v40
	v_fma_f32 v59, v45, v59, v41
	v_fma_f32 v60, v46, v60, v50
	v_fma_f32 v61, v47, v61, v51
	v_fma_f32 v62, v48, v62, v52
	v_fma_f32 v63, v49, v63, v53
	v_cvt_pk_bf16_f32 v64, v56, v57
	v_cvt_pk_bf16_f32 v65, v58, v59
	v_cvt_pk_bf16_f32 v66, v60, v61
	v_cvt_pk_bf16_f32 v67, v62, v63
	ds_write_b128 v212, v[64:67] offset:18432
	ds_write_b128 v213, v[24:27] offset:17408
	s_waitcnt lgkmcnt(6)
	v_lshlrev_b32_e32 v56, 16, v12
	v_and_b32_e32 v57, 0xffff0000, v12
	v_lshlrev_b32_e32 v58, 16, v13
	v_and_b32_e32 v59, 0xffff0000, v13
	v_lshlrev_b32_e32 v60, 16, v14
	v_and_b32_e32 v61, 0xffff0000, v14
	v_lshlrev_b32_e32 v62, 16, v15
	v_and_b32_e32 v63, 0xffff0000, v15
	v_sub_f32_e32 v56, v56, v94
	v_sub_f32_e32 v57, v57, v94
	v_sub_f32_e32 v58, v58, v94
	v_sub_f32_e32 v59, v59, v94
	v_sub_f32_e32 v60, v60, v94
	v_sub_f32_e32 v61, v61, v94
	v_sub_f32_e32 v62, v62, v94
	v_sub_f32_e32 v63, v63, v94
	v_mul_f32_e32 v56, v95, v56
	v_mul_f32_e32 v57, v95, v57
	v_mul_f32_e32 v58, v95, v58
	v_mul_f32_e32 v59, v95, v59
	v_mul_f32_e32 v60, v95, v60
	v_mul_f32_e32 v61, v95, v61
	v_mul_f32_e32 v62, v95, v62
	v_mul_f32_e32 v63, v95, v63
	v_fma_f32 v56, v42, v56, v38
	v_fma_f32 v57, v43, v57, v39
	v_fma_f32 v58, v44, v58, v40
	v_fma_f32 v59, v45, v59, v41
	v_fma_f32 v60, v46, v60, v50
	v_fma_f32 v61, v47, v61, v51
	v_fma_f32 v62, v48, v62, v52
	v_fma_f32 v63, v49, v63, v53
	v_cvt_pk_bf16_f32 v64, v56, v57
	v_cvt_pk_bf16_f32 v65, v58, v59
	v_cvt_pk_bf16_f32 v66, v60, v61
	v_cvt_pk_bf16_f32 v67, v62, v63
	ds_write_b128 v212, v[64:67] offset:27648
	ds_write_b128 v213, v[28:31] offset:26112
	s_waitcnt lgkmcnt(0)
	s_barrier
	ds_read2_b64 v[12:15], v217 offset1:4
	ds_read2_b64 v[8:11], v217 offset0:8 offset1:12
	ds_read2_b64 v[0:3], v217 offset0:16 offset1:20
	ds_read2_b64 v[4:7], v217 offset0:24 offset1:28
	ds_read_b64_tr_b16 v[18:19], v216
	ds_read_b64_tr_b16 v[20:21], v216 offset:4608
	ds_read_b64_tr_b16 v[22:23], v216 offset:9216
	ds_read_b64_tr_b16 v[24:25], v216 offset:13824
	ds_read_b64_tr_b16 v[26:27], v216 offset:18432
	ds_read_b64_tr_b16 v[28:29], v216 offset:23040
	ds_read_b64_tr_b16 v[30:31], v216 offset:27648
	ds_read_b64_tr_b16 v[32:33], v216 offset:32256
	s_waitcnt lgkmcnt(0)
	ds_read_b64_tr_b16 v[54:55], v216 offset:32
	ds_read_b64_tr_b16 v[56:57], v216 offset:4640
	ds_read_b64_tr_b16 v[58:59], v216 offset:9248
	ds_read_b64_tr_b16 v[60:61], v216 offset:13856
	ds_read_b64_tr_b16 v[62:63], v216 offset:18464
	ds_read_b64_tr_b16 v[64:65], v216 offset:23072
	ds_read_b64_tr_b16 v[66:67], v216 offset:27680
	ds_read_b64_tr_b16 v[68:69], v216 offset:32288
	v_mfma_f32_16x16x32_bf16 v[34:37], v[18:21], v[12:15], 0
	v_mfma_f32_16x16x32_bf16 v[34:37], v[22:25], v[8:11], v[34:37]
	v_mfma_f32_16x16x32_bf16 v[34:37], v[26:29], v[0:3], v[34:37]
	v_mfma_f32_16x16x32_bf16 v[34:37], v[30:33], v[4:7], v[34:37]
	s_waitcnt lgkmcnt(0)
	ds_read_b64_tr_b16 v[18:19], v216 offset:64
	ds_read_b64_tr_b16 v[20:21], v216 offset:4672
	ds_read_b64_tr_b16 v[22:23], v216 offset:9280
	ds_read_b64_tr_b16 v[24:25], v216 offset:13888
	ds_read_b64_tr_b16 v[26:27], v216 offset:18496
	ds_read_b64_tr_b16 v[28:29], v216 offset:23104
	ds_read_b64_tr_b16 v[30:31], v216 offset:27712
	ds_read_b64_tr_b16 v[32:33], v216 offset:32320
	v_mfma_f32_16x16x32_bf16 v[88:91], v[54:57], v[12:15], 0
	v_lshlrev_b32_e32 v38, 16, v70
	v_and_b32_e32 v39, 0xffff0000, v70
	v_lshlrev_b32_e32 v40, 16, v71
	v_and_b32_e32 v41, 0xffff0000, v71
	v_mfma_f32_16x16x32_bf16 v[88:91], v[58:61], v[8:11], v[88:91]
	v_add_f32_e32 v42, v86, v34
	v_add_f32_e32 v43, v86, v35
	v_add_f32_e32 v44, v86, v36
	v_add_f32_e32 v45, v86, v37
	v_mfma_f32_16x16x32_bf16 v[88:91], v[62:65], v[0:3], v[88:91]
	v_mul_f32_e32 v42, v42, v38
	v_mul_f32_e32 v43, v43, v39
	v_mul_f32_e32 v44, v44, v40
	v_mul_f32_e32 v45, v45, v41
	v_mfma_f32_16x16x32_bf16 v[88:91], v[66:69], v[4:7], v[88:91]
	v_cvt_pk_bf16_f32 v46, v42, v43
	v_cvt_pk_bf16_f32 v47, v44, v45
	global_store_dwordx2 v211, v[46:47], s[12:13]
	s_waitcnt lgkmcnt(0)
	ds_read_b64_tr_b16 v[54:55], v216 offset:96
	ds_read_b64_tr_b16 v[56:57], v216 offset:4704
	ds_read_b64_tr_b16 v[58:59], v216 offset:9312
	ds_read_b64_tr_b16 v[60:61], v216 offset:13920
	ds_read_b64_tr_b16 v[62:63], v216 offset:18528
	ds_read_b64_tr_b16 v[64:65], v216 offset:23136
	ds_read_b64_tr_b16 v[66:67], v216 offset:27744
	ds_read_b64_tr_b16 v[68:69], v216 offset:32352
	v_mfma_f32_16x16x32_bf16 v[34:37], v[18:21], v[12:15], 0
	v_lshlrev_b32_e32 v38, 16, v72
	v_and_b32_e32 v39, 0xffff0000, v72
	v_lshlrev_b32_e32 v40, 16, v73
	v_and_b32_e32 v41, 0xffff0000, v73
	v_mfma_f32_16x16x32_bf16 v[34:37], v[22:25], v[8:11], v[34:37]
	v_add_f32_e32 v42, v86, v88
	v_add_f32_e32 v43, v86, v89
	v_add_f32_e32 v44, v86, v90
	v_add_f32_e32 v45, v86, v91
	v_mfma_f32_16x16x32_bf16 v[34:37], v[26:29], v[0:3], v[34:37]
	v_mul_f32_e32 v42, v42, v38
	v_mul_f32_e32 v43, v43, v39
	v_mul_f32_e32 v44, v44, v40
	v_mul_f32_e32 v45, v45, v41
	v_mfma_f32_16x16x32_bf16 v[34:37], v[30:33], v[4:7], v[34:37]
	v_cvt_pk_bf16_f32 v48, v42, v43
	v_cvt_pk_bf16_f32 v49, v44, v45
	global_store_dwordx2 v211, v[48:49], s[12:13] offset:32
	s_waitcnt lgkmcnt(0)
	ds_read_b64_tr_b16 v[18:19], v216 offset:128
	ds_read_b64_tr_b16 v[20:21], v216 offset:4736
	ds_read_b64_tr_b16 v[22:23], v216 offset:9344
	ds_read_b64_tr_b16 v[24:25], v216 offset:13952
	ds_read_b64_tr_b16 v[26:27], v216 offset:18560
	ds_read_b64_tr_b16 v[28:29], v216 offset:23168
	ds_read_b64_tr_b16 v[30:31], v216 offset:27776
	ds_read_b64_tr_b16 v[32:33], v216 offset:32384
	v_mfma_f32_16x16x32_bf16 v[88:91], v[54:57], v[12:15], 0
	v_lshlrev_b32_e32 v38, 16, v74
	v_and_b32_e32 v39, 0xffff0000, v74
	v_lshlrev_b32_e32 v40, 16, v75
	v_and_b32_e32 v41, 0xffff0000, v75
	v_mfma_f32_16x16x32_bf16 v[88:91], v[58:61], v[8:11], v[88:91]
	v_add_f32_e32 v42, v86, v34
	v_add_f32_e32 v43, v86, v35
	v_add_f32_e32 v44, v86, v36
	v_add_f32_e32 v45, v86, v37
	v_mfma_f32_16x16x32_bf16 v[88:91], v[62:65], v[0:3], v[88:91]
	v_mul_f32_e32 v42, v42, v38
	v_mul_f32_e32 v43, v43, v39
	v_mul_f32_e32 v44, v44, v40
	v_mul_f32_e32 v45, v45, v41
	v_mfma_f32_16x16x32_bf16 v[88:91], v[66:69], v[4:7], v[88:91]
	v_cvt_pk_bf16_f32 v46, v42, v43
	v_cvt_pk_bf16_f32 v47, v44, v45
	global_store_dwordx2 v211, v[46:47], s[12:13] offset:64
	s_waitcnt lgkmcnt(0)
	ds_read_b64_tr_b16 v[54:55], v216 offset:160
	ds_read_b64_tr_b16 v[56:57], v216 offset:4768
	ds_read_b64_tr_b16 v[58:59], v216 offset:9376
	ds_read_b64_tr_b16 v[60:61], v216 offset:13984
	ds_read_b64_tr_b16 v[62:63], v216 offset:18592
	ds_read_b64_tr_b16 v[64:65], v216 offset:23200
	ds_read_b64_tr_b16 v[66:67], v216 offset:27808
	ds_read_b64_tr_b16 v[68:69], v216 offset:32416
	v_mfma_f32_16x16x32_bf16 v[34:37], v[18:21], v[12:15], 0
	v_lshlrev_b32_e32 v38, 16, v76
	v_and_b32_e32 v39, 0xffff0000, v76
	v_lshlrev_b32_e32 v40, 16, v77
	v_and_b32_e32 v41, 0xffff0000, v77
	v_mfma_f32_16x16x32_bf16 v[34:37], v[22:25], v[8:11], v[34:37]
	v_add_f32_e32 v42, v86, v88
	v_add_f32_e32 v43, v86, v89
	v_add_f32_e32 v44, v86, v90
	v_add_f32_e32 v45, v86, v91
	v_mfma_f32_16x16x32_bf16 v[34:37], v[26:29], v[0:3], v[34:37]
	v_mul_f32_e32 v42, v42, v38
	v_mul_f32_e32 v43, v43, v39
	v_mul_f32_e32 v44, v44, v40
	v_mul_f32_e32 v45, v45, v41
	v_mfma_f32_16x16x32_bf16 v[34:37], v[30:33], v[4:7], v[34:37]
	v_cvt_pk_bf16_f32 v48, v42, v43
	v_cvt_pk_bf16_f32 v49, v44, v45
	global_store_dwordx2 v211, v[48:49], s[12:13] offset:96
	s_waitcnt lgkmcnt(0)
	ds_read_b64_tr_b16 v[18:19], v216 offset:192
	ds_read_b64_tr_b16 v[20:21], v216 offset:4800
	ds_read_b64_tr_b16 v[22:23], v216 offset:9408
	ds_read_b64_tr_b16 v[24:25], v216 offset:14016
	ds_read_b64_tr_b16 v[26:27], v216 offset:18624
	ds_read_b64_tr_b16 v[28:29], v216 offset:23232
	ds_read_b64_tr_b16 v[30:31], v216 offset:27840
	ds_read_b64_tr_b16 v[32:33], v216 offset:32448
	v_mfma_f32_16x16x32_bf16 v[88:91], v[54:57], v[12:15], 0
	v_lshlrev_b32_e32 v38, 16, v78
	v_and_b32_e32 v39, 0xffff0000, v78
	v_lshlrev_b32_e32 v40, 16, v79
	v_and_b32_e32 v41, 0xffff0000, v79
	v_mfma_f32_16x16x32_bf16 v[88:91], v[58:61], v[8:11], v[88:91]
	v_add_f32_e32 v42, v86, v34
	v_add_f32_e32 v43, v86, v35
	v_add_f32_e32 v44, v86, v36
	v_add_f32_e32 v45, v86, v37
	v_mfma_f32_16x16x32_bf16 v[88:91], v[62:65], v[0:3], v[88:91]
	v_mul_f32_e32 v42, v42, v38
	v_mul_f32_e32 v43, v43, v39
	v_mul_f32_e32 v44, v44, v40
	v_mul_f32_e32 v45, v45, v41
	v_mfma_f32_16x16x32_bf16 v[88:91], v[66:69], v[4:7], v[88:91]
	v_cvt_pk_bf16_f32 v46, v42, v43
	v_cvt_pk_bf16_f32 v47, v44, v45
	global_store_dwordx2 v211, v[46:47], s[12:13] offset:128
	s_waitcnt lgkmcnt(0)
	ds_read_b64_tr_b16 v[54:55], v216 offset:224
	ds_read_b64_tr_b16 v[56:57], v216 offset:4832
	ds_read_b64_tr_b16 v[58:59], v216 offset:9440
	ds_read_b64_tr_b16 v[60:61], v216 offset:14048
	ds_read_b64_tr_b16 v[62:63], v216 offset:18656
	ds_read_b64_tr_b16 v[64:65], v216 offset:23264
	ds_read_b64_tr_b16 v[66:67], v216 offset:27872
	ds_read_b64_tr_b16 v[68:69], v216 offset:32480
	v_mfma_f32_16x16x32_bf16 v[34:37], v[18:21], v[12:15], 0
	v_lshlrev_b32_e32 v38, 16, v80
	v_and_b32_e32 v39, 0xffff0000, v80
	v_lshlrev_b32_e32 v40, 16, v81
	v_and_b32_e32 v41, 0xffff0000, v81
	v_mfma_f32_16x16x32_bf16 v[34:37], v[22:25], v[8:11], v[34:37]
	v_add_f32_e32 v42, v86, v88
	v_add_f32_e32 v43, v86, v89
	v_add_f32_e32 v44, v86, v90
	v_add_f32_e32 v45, v86, v91
	v_mfma_f32_16x16x32_bf16 v[34:37], v[26:29], v[0:3], v[34:37]
	v_mul_f32_e32 v42, v42, v38
	v_mul_f32_e32 v43, v43, v39
	v_mul_f32_e32 v44, v44, v40
	v_mul_f32_e32 v45, v45, v41
	v_mfma_f32_16x16x32_bf16 v[34:37], v[30:33], v[4:7], v[34:37]
	v_cvt_pk_bf16_f32 v48, v42, v43
	v_cvt_pk_bf16_f32 v49, v44, v45
	global_store_dwordx2 v211, v[48:49], s[12:13] offset:160
	s_waitcnt lgkmcnt(0)
	v_mfma_f32_16x16x32_bf16 v[88:91], v[54:57], v[12:15], 0
	v_lshlrev_b32_e32 v38, 16, v82
	v_and_b32_e32 v39, 0xffff0000, v82
	v_lshlrev_b32_e32 v40, 16, v83
	v_and_b32_e32 v41, 0xffff0000, v83
	v_mfma_f32_16x16x32_bf16 v[88:91], v[58:61], v[8:11], v[88:91]
	v_add_f32_e32 v42, v86, v34
	v_add_f32_e32 v43, v86, v35
	v_add_f32_e32 v44, v86, v36
	v_add_f32_e32 v45, v86, v37
	v_mfma_f32_16x16x32_bf16 v[88:91], v[62:65], v[0:3], v[88:91]
	v_mul_f32_e32 v42, v42, v38
	v_mul_f32_e32 v43, v43, v39
	v_mul_f32_e32 v44, v44, v40
	v_mul_f32_e32 v45, v45, v41
	v_mfma_f32_16x16x32_bf16 v[88:91], v[66:69], v[4:7], v[88:91]
	v_cvt_pk_bf16_f32 v46, v42, v43
	v_cvt_pk_bf16_f32 v47, v44, v45
	global_store_dwordx2 v211, v[46:47], s[12:13] offset:192
	v_lshlrev_b32_e32 v38, 16, v84
	v_and_b32_e32 v39, 0xffff0000, v84
	v_lshlrev_b32_e32 v40, 16, v85
	v_and_b32_e32 v41, 0xffff0000, v85
	s_nop 3
	v_add_f32_e32 v42, v86, v88
	v_add_f32_e32 v43, v86, v89
	v_add_f32_e32 v44, v86, v90
	v_add_f32_e32 v45, v86, v91
	v_mul_f32_e32 v42, v42, v38
	v_mul_f32_e32 v43, v43, v39
	v_mul_f32_e32 v44, v44, v40
	v_mul_f32_e32 v45, v45, v41
	v_cvt_pk_bf16_f32 v48, v42, v43
	v_cvt_pk_bf16_f32 v49, v44, v45
	global_store_dwordx2 v211, v[48:49], s[12:13] offset:224
	s_add_i32 s5, s5, 1
	s_add_i32 s3, s3, -1
	s_cmp_gt_u32 s3, 0
	s_cbranch_scc1 .Lcma_top

.LBB0_890:
	v_readlane_b32 s4, v254, 39
	s_cmpk_lt_u32 s2, 0x80
	v_readlane_b32 s5, v254, 40
	s_cselect_b64 s[0:1], -1, 0
	s_xor_b64 s[4:5], s[4:5], -1
	s_or_b64 s[0:1], s[0:1], s[4:5]
	s_movk_i32 s3, 0x80
	s_and_b64 vcc, exec, s[0:1]
	s_cbranch_vccnz .LBB0_895
	s_cmpk_lt_i32 s2, 0x80
	s_cbranch_scc1 .LBB0_895
	s_mul_i32 s5, s2, 5
	s_add_i32 s5, s5, 0
	s_mov_b32 s3, 5
	s_add_u32 s8, s30, 0x800000
	s_addc_u32 s9, s31, 0
	s_mov_b32 s4, 0x3a800000
	v_readlane_b32 s36, v254, 21
	v_readlane_b32 s37, v254, 22
	v_readlane_b32 s38, v254, 19
	v_readlane_b32 s39, v254, 20
	v_readlane_b32 s40, v254, 25
	v_readlane_b32 s41, v254, 26
	v_readlane_b32 s42, v254, 41
	v_readlane_b32 s43, v254, 42
	v_readlane_b32 s44, v254, 43
	v_readlane_b32 s45, v254, 44
	v_readlane_b32 s96, v254, 45
	v_readlane_b32 s97, v254, 46
	v_and_b32_e32 v1, 15, v195
	v_lshrrev_b32_e32 v0, 4, v195
	v_lshlrev_b32_e32 v2, 4, v1
	v_lshl_add_u32 v200, v0, 11, v2
	v_add_u32_e32 v201, 0x10000, v200
	v_add_u32_e32 v202, 0x20000, v200
	v_add_u32_e32 v203, 0x30000, v200
	v_lshl_add_u32 v204, v0, 8, v2
	v_add_u32_e32 v205, 0x2000, v204
	v_add_u32_e32 v206, 0x4000, v204
	v_add_u32_e32 v207, 0x6000, v204
	v_and_b32_e32 v3, 0x7f, v195
	v_lshlrev_b32_e32 v208, 7, v3
	v_lshlrev_b32_e32 v209, 5, v1
	v_lshrrev_b32_e32 v4, 6, v195
	v_lshl_add_u32 v5, v4, 4, v1
	v_lshlrev_b32_e32 v210, 2, v5
	v_bfe_u32 v6, v195, 4, 2
	v_lshlrev_b32_e32 v7, 3, v6
	v_lshl_add_u32 v211, v5, 11, v7
	v_mul_u32_u24_e32 v8, 0x120, v0
	v_add_u32_e32 v212, v8, v2
	v_mul_u32_u24_e32 v8, 0x110, v0
	v_add_u32_e32 v8, v8, v2
	v_add_u32_e32 v213, 0x9000, v8
	v_lshlrev_b32_e32 v8, 3, v0
	v_add_u32_e32 v214, 0x11800, v8
	v_lshlrev_b32_e32 v8, 3, v195
	v_add_u32_e32 v215, 0x11800, v8
	v_lshrrev_b32_e32 v8, 2, v1
	v_lshl_or_b32 v8, v6, 2, v8
	v_mul_u32_u24_e32 v8, 0x120, v8
	v_and_b32_e32 v9, 3, v195
	v_lshl_add_u32 v216, v9, 3, v8
	v_mul_u32_u24_e32 v8, 0x110, v5
	v_add_u32_e32 v8, v8, v7
	v_add_u32_e32 v217, 0x9000, v8
	s_mov_b32 s0, s5
	s_and_b32 s1, s0, 7
	s_lshr_b32 s0, s0, 3
	s_lshl_b32 s0, s0, 7
	s_lshl_b32 s10, s1, 8
	s_lshl_b32 s11, s0, 11
	s_add_u32 s11, s11, s10
	s_add_u32 s46, s42, s11
	s_addc_u32 s47, s43, 0
	s_add_u32 s6, s96, s11
	s_addc_u32 s7, s97, 0
	s_lshl_b32 s10, s1, 15
	s_add_u32 s48, s8, s10
	s_addc_u32 s49, s9, 0
	s_lshl_b32 s10, s0, 7
	s_add_u32 s50, s44, s10
	s_addc_u32 s51, s45, 0
	s_lshl_b32 s10, s1, 9
	s_add_u32 s14, s36, s10
	s_addc_u32 s15, s37, 0
	s_add_u32 s16, s38, s10
	s_addc_u32 s17, s39, 0
	s_add_u32 s10, s40, s10
	s_addc_u32 s11, s41, 0
	v_readfirstlane_b32 s0, v195
	s_nop 1
	s_cmp_lt_u32 s0, 0x80
	s_cbranch_scc0 .Lcmb_pf0
	global_load_dwordx4 v[132:135], v208, s[50:51]
	global_load_dwordx4 v[136:139], v208, s[50:51] offset:16
	global_load_dwordx4 v[140:143], v208, s[50:51] offset:32
	global_load_dwordx4 v[144:147], v208, s[50:51] offset:48
	global_load_dwordx4 v[148:151], v208, s[50:51] offset:64
	global_load_dwordx4 v[152:155], v208, s[50:51] offset:80
	global_load_dwordx4 v[156:159], v208, s[50:51] offset:96
	global_load_dwordx4 v[160:163], v208, s[50:51] offset:112

.Lcmb_pf1:
	global_load_dwordx4 v[100:103], v200, s[46:47]
	global_load_dwordx4 v[116:119], v204, s[48:49]
	global_load_dwordx4 v[104:107], v201, s[46:47]
	global_load_dwordx4 v[120:123], v205, s[48:49]
	global_load_dwordx4 v[108:111], v202, s[46:47]
	global_load_dwordx4 v[124:127], v206, s[48:49]
	global_load_dwordx4 v[112:115], v203, s[46:47]
	global_load_dwordx4 v[128:131], v207, s[48:49]
	global_load_dwordx4 v[164:167], v209, s[14:15]
	global_load_dwordx4 v[168:171], v209, s[16:17]
	global_load_dwordx4 v[172:175], v209, s[16:17] offset:16
	global_load_dwordx4 v[176:179], v209, s[14:15] offset:16
	global_load_dword v236, v210, s[10:11]
	global_load_dwordx2 v[220:221], v211, s[6:7]
	global_load_dwordx2 v[222:223], v211, s[6:7] offset:32
	global_load_dwordx2 v[224:225], v211, s[6:7] offset:64
	global_load_dwordx2 v[226:227], v211, s[6:7] offset:96
	global_load_dwordx2 v[228:229], v211, s[6:7] offset:128
	global_load_dwordx2 v[230:231], v211, s[6:7] offset:160
	global_load_dwordx2 v[232:233], v211, s[6:7] offset:192
	global_load_dwordx2 v[234:235], v211, s[6:7] offset:224
.Lcmb_nopf:
	s_waitcnt lgkmcnt(0)
	s_barrier
	ds_read_b64 v[88:89], v214
	ds_read_b64 v[90:91], v214 offset:256
	ds_read_b64 v[92:93], v214 offset:512
	ds_read_b64 v[94:95], v214 offset:768
	s_waitcnt lgkmcnt(3)
	v_lshlrev_b32_e32 v56, 16, v0
	v_and_b32_e32 v57, 0xffff0000, v0
	v_lshlrev_b32_e32 v58, 16, v1
	v_and_b32_e32 v59, 0xffff0000, v1
	v_lshlrev_b32_e32 v60, 16, v2
	v_and_b32_e32 v61, 0xffff0000, v2
	v_lshlrev_b32_e32 v62, 16, v3
	v_and_b32_e32 v63, 0xffff0000, v3
	v_sub_f32_e32 v56, v56, v88
	v_sub_f32_e32 v57, v57, v88
	v_sub_f32_e32 v58, v58, v88
	v_sub_f32_e32 v59, v59, v88
	v_sub_f32_e32 v60, v60, v88
	v_sub_f32_e32 v61, v61, v88
	v_sub_f32_e32 v62, v62, v88
	v_sub_f32_e32 v63, v63, v88
	v_mul_f32_e32 v56, v89, v56
	v_mul_f32_e32 v57, v89, v57
	v_mul_f32_e32 v58, v89, v58
	v_mul_f32_e32 v59, v89, v59
	v_mul_f32_e32 v60, v89, v60
	v_mul_f32_e32 v61, v89, v61
	v_mul_f32_e32 v62, v89, v62
	v_mul_f32_e32 v63, v89, v63
	v_fma_f32 v56, v42, v56, v38
	v_fma_f32 v57, v43, v57, v39
	v_fma_f32 v58, v44, v58, v40
	v_fma_f32 v59, v45, v59, v41
	v_fma_f32 v60, v46, v60, v50
	v_fma_f32 v61, v47, v61, v51
	v_fma_f32 v62, v48, v62, v52
	v_fma_f32 v63, v49, v63, v53
	v_cvt_pk_bf16_f32 v64, v56, v57
	v_cvt_pk_bf16_f32 v65, v58, v59
	v_cvt_pk_bf16_f32 v66, v60, v61
	v_cvt_pk_bf16_f32 v67, v62, v63
	ds_write_b128 v212, v[64:67]
	ds_write_b128 v213, v[16:19]
	s_waitcnt lgkmcnt(4)
	v_lshlrev_b32_e32 v56, 16, v4
	v_and_b32_e32 v57, 0xffff0000, v4
	v_lshlrev_b32_e32 v58, 16, v5
	v_and_b32_e32 v59, 0xffff0000, v5
	v_lshlrev_b32_e32 v60, 16, v6
	v_and_b32_e32 v61, 0xffff0000, v6
	v_lshlrev_b32_e32 v62, 16, v7
	v_and_b32_e32 v63, 0xffff0000, v7
	v_sub_f32_e32 v56, v56, v90
	v_sub_f32_e32 v57, v57, v90
	v_sub_f32_e32 v58, v58, v90
	v_sub_f32_e32 v59, v59, v90
	v_sub_f32_e32 v60, v60, v90
	v_sub_f32_e32 v61, v61, v90
	v_sub_f32_e32 v62, v62, v90
	v_sub_f32_e32 v63, v63, v90
	v_mul_f32_e32 v56, v91, v56
	v_mul_f32_e32 v57, v91, v57
	v_mul_f32_e32 v58, v91, v58
	v_mul_f32_e32 v59, v91, v59
	v_mul_f32_e32 v60, v91, v60
	v_mul_f32_e32 v61, v91, v61
	v_mul_f32_e32 v62, v91, v62
	v_mul_f32_e32 v63, v91, v63
	v_fma_f32 v56, v42, v56, v38
	v_fma_f32 v57, v43, v57, v39
	v_fma_f32 v58, v44, v58, v40
	v_fma_f32 v59, v45, v59, v41
	v_fma_f32 v60, v46, v60, v50
	v_fma_f32 v61, v47, v61, v51
	v_fma_f32 v62, v48, v62, v52
	v_fma_f32 v63, v49, v63, v53
	v_cvt_pk_bf16_f32 v64, v56, v57
	v_cvt_pk_bf16_f32 v65, v58, v59
	v_cvt_pk_bf16_f32 v66, v60, v61
	v_cvt_pk_bf16_f32 v67, v62, v63
	ds_write_b128 v212, v[64:67] offset:9216
	ds_write_b128 v213, v[20:23] offset:8704
	s_waitcnt lgkmcnt(5)
	v_lshlrev_b32_e32 v56, 16, v8
	v_and_b32_e32 v57, 0xffff0000, v8
	v_lshlrev_b32_e32 v58, 16, v9
	v_and_b32_e32 v59, 0xffff0000, v9
	v_lshlrev_b32_e32 v60, 16, v10
	v_and_b32_e32 v61, 0xffff0000, v10
	v_lshlrev_b32_e32 v62, 16, v11
	v_and_b32_e32 v63, 0xffff0000, v11
	v_sub_f32_e32 v56, v56, v92
	v_sub_f32_e32 v57, v57, v92
	v_sub_f32_e32 v58, v58, v92
	v_sub_f32_e32 v59, v59, v92
	v_sub_f32_e32 v60, v60, v92
	v_sub_f32_e32 v61, v61, v92
	v_sub_f32_e32 v62, v62, v92
	v_sub_f32_e32 v63, v63, v92
	v_mul_f32_e32 v56, v93, v56
	v_mul_f32_e32 v57, v93, v57
	v_mul_f32_e32 v58, v93, v58
	v_mul_f32_e32 v59, v93, v59
	v_mul_f32_e32 v60, v93, v60
	v_mul_f32_e32 v61, v93, v61
	v_mul_f32_e32 v62, v93, v62
	v_mul_f32_e32 v63, v93, v63
	v_fma_f32 v56, v42, v56, v38
	v_fma_f32 v57, v43, v57, v39
	v_fma_f32 v58, v44, v58, v40
	v_fma_f32 v59, v45, v59, v41
	v_fma_f32 v60, v46, v60, v50
	v_fma_f32 v61, v47, v61, v51
	v_fma_f32 v62, v48, v62, v52
	v_fma_f32 v63, v49, v63, v53
	v_cvt_pk_bf16_f32 v64, v56, v57
	v_cvt_pk_bf16_f32 v65, v58, v59
	v_cvt_pk_bf16_f32 v66, v60, v61
	v_cvt_pk_bf16_f32 v67, v62, v63
	ds_write_b128 v212, v[64:67] offset:18432
	ds_write_b128 v213, v[24:27] offset:17408
	s_waitcnt lgkmcnt(6)
	v_lshlrev_b32_e32 v56, 16, v12
	v_and_b32_e32 v57, 0xffff0000, v12
	v_lshlrev_b32_e32 v58, 16, v13
	v_and_b32_e32 v59, 0xffff0000, v13
	v_lshlrev_b32_e32 v60, 16, v14
	v_and_b32_e32 v61, 0xffff0000, v14
	v_lshlrev_b32_e32 v62, 16, v15
	v_and_b32_e32 v63, 0xffff0000, v15
	v_sub_f32_e32 v56, v56, v94
	v_sub_f32_e32 v57, v57, v94
	v_sub_f32_e32 v58, v58, v94
	v_sub_f32_e32 v59, v59, v94
	v_sub_f32_e32 v60, v60, v94
	v_sub_f32_e32 v61, v61, v94
	v_sub_f32_e32 v62, v62, v94
	v_sub_f32_e32 v63, v63, v94
	v_mul_f32_e32 v56, v95, v56
	v_mul_f32_e32 v57, v95, v57
	v_mul_f32_e32 v58, v95, v58
	v_mul_f32_e32 v59, v95, v59
	v_mul_f32_e32 v60, v95, v60
	v_mul_f32_e32 v61, v95, v61
	v_mul_f32_e32 v62, v95, v62
	v_mul_f32_e32 v63, v95, v63
	v_fma_f32 v56, v42, v56, v38
	v_fma_f32 v57, v43, v57, v39
	v_fma_f32 v58, v44, v58, v40
	v_fma_f32 v59, v45, v59, v41
	v_fma_f32 v60, v46, v60, v50
	v_fma_f32 v61, v47, v61, v51
	v_fma_f32 v62, v48, v62, v52
	v_fma_f32 v63, v49, v63, v53
	v_cvt_pk_bf16_f32 v64, v56, v57
	v_cvt_pk_bf16_f32 v65, v58, v59
	v_cvt_pk_bf16_f32 v66, v60, v61
	v_cvt_pk_bf16_f32 v67, v62, v63
	ds_write_b128 v212, v[64:67] offset:27648
	ds_write_b128 v213, v[28:31] offset:26112
	s_waitcnt lgkmcnt(0)
	s_barrier
	ds_read2_b64 v[12:15], v217 offset1:4
	ds_read2_b64 v[8:11], v217 offset0:8 offset1:12
	ds_read2_b64 v[0:3], v217 offset0:16 offset1:20
	ds_read2_b64 v[4:7], v217 offset0:24 offset1:28
	ds_read_b64_tr_b16 v[18:19], v216
	ds_read_b64_tr_b16 v[20:21], v216 offset:4608
	ds_read_b64_tr_b16 v[22:23], v216 offset:9216
	ds_read_b64_tr_b16 v[24:25], v216 offset:13824
	ds_read_b64_tr_b16 v[26:27], v216 offset:18432
	ds_read_b64_tr_b16 v[28:29], v216 offset:23040
	ds_read_b64_tr_b16 v[30:31], v216 offset:27648
	ds_read_b64_tr_b16 v[32:33], v216 offset:32256
	s_waitcnt lgkmcnt(0)
	ds_read_b64_tr_b16 v[54:55], v216 offset:32
	ds_read_b64_tr_b16 v[56:57], v216 offset:4640
	ds_read_b64_tr_b16 v[58:59], v216 offset:9248
	ds_read_b64_tr_b16 v[60:61], v216 offset:13856
	ds_read_b64_tr_b16 v[62:63], v216 offset:18464
	ds_read_b64_tr_b16 v[64:65], v216 offset:23072
	ds_read_b64_tr_b16 v[66:67], v216 offset:27680
	ds_read_b64_tr_b16 v[68:69], v216 offset:32288
	v_mfma_f32_16x16x32_bf16 v[34:37], v[18:21], v[12:15], 0
	v_mfma_f32_16x16x32_bf16 v[34:37], v[22:25], v[8:11], v[34:37]
	v_mfma_f32_16x16x32_bf16 v[34:37], v[26:29], v[0:3], v[34:37]
	v_mfma_f32_16x16x32_bf16 v[34:37], v[30:33], v[4:7], v[34:37]
	s_waitcnt lgkmcnt(0)
	ds_read_b64_tr_b16 v[18:19], v216 offset:64
	ds_read_b64_tr_b16 v[20:21], v216 offset:4672
	ds_read_b64_tr_b16 v[22:23], v216 offset:9280
	ds_read_b64_tr_b16 v[24:25], v216 offset:13888
	ds_read_b64_tr_b16 v[26:27], v216 offset:18496
	ds_read_b64_tr_b16 v[28:29], v216 offset:23104
	ds_read_b64_tr_b16 v[30:31], v216 offset:27712
	ds_read_b64_tr_b16 v[32:33], v216 offset:32320
	v_mfma_f32_16x16x32_bf16 v[88:91], v[54:57], v[12:15], 0
	v_lshlrev_b32_e32 v38, 16, v70
	v_and_b32_e32 v39, 0xffff0000, v70
	v_lshlrev_b32_e32 v40, 16, v71
	v_and_b32_e32 v41, 0xffff0000, v71
	v_mfma_f32_16x16x32_bf16 v[88:91], v[58:61], v[8:11], v[88:91]
	v_add_f32_e32 v42, v86, v34
	v_add_f32_e32 v43, v86, v35
	v_add_f32_e32 v44, v86, v36
	v_add_f32_e32 v45, v86, v37
	v_mfma_f32_16x16x32_bf16 v[88:91], v[62:65], v[0:3], v[88:91]
	v_mul_f32_e32 v42, v42, v38
	v_mul_f32_e32 v43, v43, v39
	v_mul_f32_e32 v44, v44, v40
	v_mul_f32_e32 v45, v45, v41
	v_mfma_f32_16x16x32_bf16 v[88:91], v[66:69], v[4:7], v[88:91]
	v_cvt_pk_bf16_f32 v46, v42, v43
	v_cvt_pk_bf16_f32 v47, v44, v45
	global_store_dwordx2 v211, v[46:47], s[12:13]
	s_waitcnt lgkmcnt(0)
	ds_read_b64_tr_b16 v[54:55], v216 offset:96
	ds_read_b64_tr_b16 v[56:57], v216 offset:4704
	ds_read_b64_tr_b16 v[58:59], v216 offset:9312
	ds_read_b64_tr_b16 v[60:61], v216 offset:13920
	ds_read_b64_tr_b16 v[62:63], v216 offset:18528
	ds_read_b64_tr_b16 v[64:65], v216 offset:23136
	ds_read_b64_tr_b16 v[66:67], v216 offset:27744
	ds_read_b64_tr_b16 v[68:69], v216 offset:32352
	v_mfma_f32_16x16x32_bf16 v[34:37], v[18:21], v[12:15], 0
	v_lshlrev_b32_e32 v38, 16, v72
	v_and_b32_e32 v39, 0xffff0000, v72
	v_lshlrev_b32_e32 v40, 16, v73
	v_and_b32_e32 v41, 0xffff0000, v73
	v_mfma_f32_16x16x32_bf16 v[34:37], v[22:25], v[8:11], v[34:37]
	v_add_f32_e32 v42, v86, v88
	v_add_f32_e32 v43, v86, v89
	v_add_f32_e32 v44, v86, v90
	v_add_f32_e32 v45, v86, v91
	v_mfma_f32_16x16x32_bf16 v[34:37], v[26:29], v[0:3], v[34:37]
	v_mul_f32_e32 v42, v42, v38
	v_mul_f32_e32 v43, v43, v39
	v_mul_f32_e32 v44, v44, v40
	v_mul_f32_e32 v45, v45, v41
	v_mfma_f32_16x16x32_bf16 v[34:37], v[30:33], v[4:7], v[34:37]
	v_cvt_pk_bf16_f32 v48, v42, v43
	v_cvt_pk_bf16_f32 v49, v44, v45
	global_store_dwordx2 v211, v[48:49], s[12:13] offset:32
	s_waitcnt lgkmcnt(0)
	ds_read_b64_tr_b16 v[18:19], v216 offset:128
	ds_read_b64_tr_b16 v[20:21], v216 offset:4736
	ds_read_b64_tr_b16 v[22:23], v216 offset:9344
	ds_read_b64_tr_b16 v[24:25], v216 offset:13952
	ds_read_b64_tr_b16 v[26:27], v216 offset:18560
	ds_read_b64_tr_b16 v[28:29], v216 offset:23168
	ds_read_b64_tr_b16 v[30:31], v216 offset:27776
	ds_read_b64_tr_b16 v[32:33], v216 offset:32384
	v_mfma_f32_16x16x32_bf16 v[88:91], v[54:57], v[12:15], 0
	v_lshlrev_b32_e32 v38, 16, v74
	v_and_b32_e32 v39, 0xffff0000, v74
	v_lshlrev_b32_e32 v40, 16, v75
	v_and_b32_e32 v41, 0xffff0000, v75
	v_mfma_f32_16x16x32_bf16 v[88:91], v[58:61], v[8:11], v[88:91]
	v_add_f32_e32 v42, v86, v34
	v_add_f32_e32 v43, v86, v35
	v_add_f32_e32 v44, v86, v36
	v_add_f32_e32 v45, v86, v37
	v_mfma_f32_16x16x32_bf16 v[88:91], v[62:65], v[0:3], v[88:91]
	v_mul_f32_e32 v42, v42, v38
	v_mul_f32_e32 v43, v43, v39
	v_mul_f32_e32 v44, v44, v40
	v_mul_f32_e32 v45, v45, v41
	v_mfma_f32_16x16x32_bf16 v[88:91], v[66:69], v[4:7], v[88:91]
	v_cvt_pk_bf16_f32 v46, v42, v43
	v_cvt_pk_bf16_f32 v47, v44, v45
	global_store_dwordx2 v211, v[46:47], s[12:13] offset:64
	s_waitcnt lgkmcnt(0)
	ds_read_b64_tr_b16 v[54:55], v216 offset:160
	ds_read_b64_tr_b16 v[56:57], v216 offset:4768
	ds_read_b64_tr_b16 v[58:59], v216 offset:9376
	ds_read_b64_tr_b16 v[60:61], v216 offset:13984
	ds_read_b64_tr_b16 v[62:63], v216 offset:18592
	ds_read_b64_tr_b16 v[64:65], v216 offset:23200
	ds_read_b64_tr_b16 v[66:67], v216 offset:27808
	ds_read_b64_tr_b16 v[68:69], v216 offset:32416
	v_mfma_f32_16x16x32_bf16 v[34:37], v[18:21], v[12:15], 0
	v_lshlrev_b32_e32 v38, 16, v76
	v_and_b32_e32 v39, 0xffff0000, v76
	v_lshlrev_b32_e32 v40, 16, v77
	v_and_b32_e32 v41, 0xffff0000, v77
	v_mfma_f32_16x16x32_bf16 v[34:37], v[22:25], v[8:11], v[34:37]
	v_add_f32_e32 v42, v86, v88
	v_add_f32_e32 v43, v86, v89
	v_add_f32_e32 v44, v86, v90
	v_add_f32_e32 v45, v86, v91
	v_mfma_f32_16x16x32_bf16 v[34:37], v[26:29], v[0:3], v[34:37]
	v_mul_f32_e32 v42, v42, v38
	v_mul_f32_e32 v43, v43, v39
	v_mul_f32_e32 v44, v44, v40
	v_mul_f32_e32 v45, v45, v41
	v_mfma_f32_16x16x32_bf16 v[34:37], v[30:33], v[4:7], v[34:37]
	v_cvt_pk_bf16_f32 v48, v42, v43
	v_cvt_pk_bf16_f32 v49, v44, v45
	global_store_dwordx2 v211, v[48:49], s[12:13] offset:96
	s_waitcnt lgkmcnt(0)
	ds_read_b64_tr_b16 v[18:19], v216 offset:192
	ds_read_b64_tr_b16 v[20:21], v216 offset:4800
	ds_read_b64_tr_b16 v[22:23], v216 offset:9408
	ds_read_b64_tr_b16 v[24:25], v216 offset:14016
	ds_read_b64_tr_b16 v[26:27], v216 offset:18624
	ds_read_b64_tr_b16 v[28:29], v216 offset:23232
	ds_read_b64_tr_b16 v[30:31], v216 offset:27840
	ds_read_b64_tr_b16 v[32:33], v216 offset:32448
	v_mfma_f32_16x16x32_bf16 v[88:91], v[54:57], v[12:15], 0
	v_lshlrev_b32_e32 v38, 16, v78
	v_and_b32_e32 v39, 0xffff0000, v78
	v_lshlrev_b32_e32 v40, 16, v79
	v_and_b32_e32 v41, 0xffff0000, v79
	v_mfma_f32_16x16x32_bf16 v[88:91], v[58:61], v[8:11], v[88:91]
	v_add_f32_e32 v42, v86, v34
	v_add_f32_e32 v43, v86, v35
	v_add_f32_e32 v44, v86, v36
	v_add_f32_e32 v45, v86, v37
	v_mfma_f32_16x16x32_bf16 v[88:91], v[62:65], v[0:3], v[88:91]
	v_mul_f32_e32 v42, v42, v38
	v_mul_f32_e32 v43, v43, v39
	v_mul_f32_e32 v44, v44, v40
	v_mul_f32_e32 v45, v45, v41
	v_mfma_f32_16x16x32_bf16 v[88:91], v[66:69], v[4:7], v[88:91]
	v_cvt_pk_bf16_f32 v46, v42, v43
	v_cvt_pk_bf16_f32 v47, v44, v45
	global_store_dwordx2 v211, v[46:47], s[12:13] offset:128
	s_waitcnt lgkmcnt(0)
	ds_read_b64_tr_b16 v[54:55], v216 offset:224
	ds_read_b64_tr_b16 v[56:57], v216 offset:4832
	ds_read_b64_tr_b16 v[58:59], v216 offset:9440
	ds_read_b64_tr_b16 v[60:61], v216 offset:14048
	ds_read_b64_tr_b16 v[62:63], v216 offset:18656
	ds_read_b64_tr_b16 v[64:65], v216 offset:23264
	ds_read_b64_tr_b16 v[66:67], v216 offset:27872
	ds_read_b64_tr_b16 v[68:69], v216 offset:32480
	v_mfma_f32_16x16x32_bf16 v[34:37], v[18:21], v[12:15], 0
	v_lshlrev_b32_e32 v38, 16, v80
	v_and_b32_e32 v39, 0xffff0000, v80
	v_lshlrev_b32_e32 v40, 16, v81
	v_and_b32_e32 v41, 0xffff0000, v81
	v_mfma_f32_16x16x32_bf16 v[34:37], v[22:25], v[8:11], v[34:37]
	v_add_f32_e32 v42, v86, v88
	v_add_f32_e32 v43, v86, v89
	v_add_f32_e32 v44, v86, v90
	v_add_f32_e32 v45, v86, v91
	v_mfma_f32_16x16x32_bf16 v[34:37], v[26:29], v[0:3], v[34:37]
	v_mul_f32_e32 v42, v42, v38
	v_mul_f32_e32 v43, v43, v39
	v_mul_f32_e32 v44, v44, v40
	v_mul_f32_e32 v45, v45, v41
	v_mfma_f32_16x16x32_bf16 v[34:37], v[30:33], v[4:7], v[34:37]
	v_cvt_pk_bf16_f32 v48, v42, v43
	v_cvt_pk_bf16_f32 v49, v44, v45
	global_store_dwordx2 v211, v[48:49], s[12:13] offset:160
	s_waitcnt lgkmcnt(0)
	v_mfma_f32_16x16x32_bf16 v[88:91], v[54:57], v[12:15], 0
	v_lshlrev_b32_e32 v38, 16, v82
	v_and_b32_e32 v39, 0xffff0000, v82
	v_lshlrev_b32_e32 v40, 16, v83
	v_and_b32_e32 v41, 0xffff0000, v83
	v_mfma_f32_16x16x32_bf16 v[88:91], v[58:61], v[8:11], v[88:91]
	v_add_f32_e32 v42, v86, v34
	v_add_f32_e32 v43, v86, v35
	v_add_f32_e32 v44, v86, v36
	v_add_f32_e32 v45, v86, v37
	v_mfma_f32_16x16x32_bf16 v[88:91], v[62:65], v[0:3], v[88:91]
	v_mul_f32_e32 v42, v42, v38
	v_mul_f32_e32 v43, v43, v39
	v_mul_f32_e32 v44, v44, v40
	v_mul_f32_e32 v45, v45, v41
	v_mfma_f32_16x16x32_bf16 v[88:91], v[66:69], v[4:7], v[88:91]
	v_cvt_pk_bf16_f32 v46, v42, v43
	v_cvt_pk_bf16_f32 v47, v44, v45
	global_store_dwordx2 v211, v[46:47], s[12:13] offset:192
	v_lshlrev_b32_e32 v38, 16, v84
	v_and_b32_e32 v39, 0xffff0000, v84
	v_lshlrev_b32_e32 v40, 16, v85
	v_and_b32_e32 v41, 0xffff0000, v85
	s_nop 3
	v_add_f32_e32 v42, v86, v88
	v_add_f32_e32 v43, v86, v89
	v_add_f32_e32 v44, v86, v90
	v_add_f32_e32 v45, v86, v91
	v_mul_f32_e32 v42, v42, v38
	v_mul_f32_e32 v43, v43, v39
	v_mul_f32_e32 v44, v44, v40
	v_mul_f32_e32 v45, v45, v41
	v_cvt_pk_bf16_f32 v48, v42, v43
	v_cvt_pk_bf16_f32 v49, v44, v45
	global_store_dwordx2 v211, v[48:49], s[12:13] offset:224
	s_add_i32 s5, s5, 1
	s_add_i32 s3, s3, -1
	s_cmp_gt_u32 s3, 0
	s_cbranch_scc1 .Lcmb_top

.LBB0_947:
	s_or_b64 exec, exec, s[0:1]
	s_waitcnt vmcnt(1)
	v_mov_b32_e32 v1, v195
	s_cmpk_lt_i32 s2, 0x200
	s_waitcnt lgkmcnt(0)
	s_barrier
	s_nop 0
	s_nop 0
	s_nop 0
	s_nop 0
	s_nop 0
	s_nop 0
	s_nop 0
	s_nop 0
	s_nop 0
	s_nop 0
	s_nop 0
	s_nop 0
	s_nop 0
	s_cselect_b64 s[4:5], -1, 0
	s_cmpk_gt_i32 s2, 0x1ff
	v_readfirstlane_b32 s3, v1
	s_cbranch_scc1 .LBB0_950
	s_and_b32 s8, s2, 7
	s_bfe_u32 s1, s2, 0x50003
	s_cmpk_gt_i32 s2, 0xff
	s_cbranch_scc0 .LBB0_951
	s_lshl_b32 s0, s8, 1
	s_bfe_u32 s6, s2, 0x10003
	s_or_b32 s0, s0, s6
	s_lshr_b32 s73, s1, 3
	s_or_b32 s0, s0, 64
	s_bfe_u32 s38, s2, 0x20004
	s_cmp_gt_u32 s1, 15
	s_cselect_b32 s6, 0x2800000, 0
	s_lshl_b32 s12, s73, 10
	s_mov_b32 s11, 0
	s_and_b32 s7, s12, 0x400
	s_or_b32 s10, s6, s7
	s_mov_b32 s13, s11
	s_mov_b32 s74, 8
	s_cbranch_execz .LBB0_952
	s_branch .LBB0_953
